# grid barrier polling switched from returning atomics to sc1 loads
# baseline (speedup 1.0000x reference)
.Lgb0_topspin:
	global_load_dword v2, v1, s[8:9] sc1
	s_waitcnt vmcnt(0)
	v_readfirstlane_b32 s7, v2
	s_cmp_gt_u32 s7, 0
	s_cbranch_scc1 .Lgb0_release
	s_sleep 1
	s_sub_i32 s11, s11, 1
	s_cmp_lg_u32 s11, 0
	s_cbranch_scc1 .Lgb0_topspin

.Lgb0_spin:
	s_sleep 1
	global_load_dword v2, v1, s[8:9] sc1
	s_waitcnt vmcnt(0)
	v_readfirstlane_b32 s7, v2
	s_cmp_gt_u32 s7, 0
	s_cbranch_scc1 .Lgb0_acq
	s_sub_i32 s11, s11, 1
	s_cmp_lg_u32 s11, 0
	s_cbranch_scc1 .Lgb0_spin

.Lgb1_topspin:
	global_load_dword v2, v1, s[8:9] sc1
	s_waitcnt vmcnt(0)
	v_readfirstlane_b32 s7, v2
	s_cmp_gt_u32 s7, 1
	s_cbranch_scc1 .Lgb1_release
	s_sleep 1
	s_sub_i32 s11, s11, 1
	s_cmp_lg_u32 s11, 0
	s_cbranch_scc1 .Lgb1_topspin

.Lgb1_spin:
	s_sleep 1
	global_load_dword v2, v1, s[8:9] sc1
	s_waitcnt vmcnt(0)
	v_readfirstlane_b32 s7, v2
	s_cmp_gt_u32 s7, 1
	s_cbranch_scc1 .Lgb1_acq
	s_sub_i32 s11, s11, 1
	s_cmp_lg_u32 s11, 0
	s_cbranch_scc1 .Lgb1_spin

.Lgb2_topspin:
	global_load_dword v2, v1, s[8:9] sc1
	s_waitcnt vmcnt(0)
	v_readfirstlane_b32 s7, v2
	s_cmp_gt_u32 s7, 2
	s_cbranch_scc1 .Lgb2_release
	s_sleep 1
	s_sub_i32 s11, s11, 1
	s_cmp_lg_u32 s11, 0
	s_cbranch_scc1 .Lgb2_topspin

.Lgb2_spin:
	s_sleep 1
	global_load_dword v2, v1, s[8:9] sc1
	s_waitcnt vmcnt(0)
	v_readfirstlane_b32 s7, v2
	s_cmp_gt_u32 s7, 2
	s_cbranch_scc1 .Lgb2_acq
	s_sub_i32 s11, s11, 1
	s_cmp_lg_u32 s11, 0
	s_cbranch_scc1 .Lgb2_spin

.Lgb3_topspin:
	global_load_dword v2, v1, s[8:9] sc1
	s_waitcnt vmcnt(0)
	v_readfirstlane_b32 s7, v2
	s_cmp_gt_u32 s7, 3
	s_cbranch_scc1 .Lgb3_release
	s_sleep 1
	s_sub_i32 s11, s11, 1
	s_cmp_lg_u32 s11, 0
	s_cbranch_scc1 .Lgb3_topspin

.Lgb3_spin:
	s_sleep 1
	global_load_dword v2, v1, s[8:9] sc1
	s_waitcnt vmcnt(0)
	v_readfirstlane_b32 s7, v2
	s_cmp_gt_u32 s7, 3
	s_cbranch_scc1 .Lgb3_acq
	s_sub_i32 s11, s11, 1
	s_cmp_lg_u32 s11, 0
	s_cbranch_scc1 .Lgb3_spin

.Lgb4_topspin:
	global_load_dword v2, v1, s[8:9] sc1
	s_waitcnt vmcnt(0)
	v_readfirstlane_b32 s7, v2
	s_cmp_gt_u32 s7, 4
	s_cbranch_scc1 .Lgb4_release
	s_sleep 1
	s_sub_i32 s11, s11, 1
	s_cmp_lg_u32 s11, 0
	s_cbranch_scc1 .Lgb4_topspin

.Lgb4_spin:
	s_sleep 1
	global_load_dword v2, v1, s[8:9] sc1
	s_waitcnt vmcnt(0)
	v_readfirstlane_b32 s7, v2
	s_cmp_gt_u32 s7, 4
	s_cbranch_scc1 .Lgb4_acq
	s_sub_i32 s11, s11, 1
	s_cmp_lg_u32 s11, 0
	s_cbranch_scc1 .Lgb4_spin

.Lgb5_topspin:
	global_load_dword v2, v1, s[8:9] sc1
	s_waitcnt vmcnt(0)
	v_readfirstlane_b32 s7, v2
	s_cmp_gt_u32 s7, 5
	s_cbranch_scc1 .Lgb5_release
	s_sleep 1
	s_sub_i32 s11, s11, 1
	s_cmp_lg_u32 s11, 0
	s_cbranch_scc1 .Lgb5_topspin

.Lgb5_spin:
	s_sleep 1
	global_load_dword v2, v1, s[8:9] sc1
	s_waitcnt vmcnt(0)
	v_readfirstlane_b32 s7, v2
	s_cmp_gt_u32 s7, 5
	s_cbranch_scc1 .Lgb5_acq
	s_sub_i32 s11, s11, 1
	s_cmp_lg_u32 s11, 0
	s_cbranch_scc1 .Lgb5_spin

.Lgb6_topspin:
	global_load_dword v2, v1, s[8:9] sc1
	s_waitcnt vmcnt(0)
	v_readfirstlane_b32 s7, v2
	s_cmp_gt_u32 s7, 6
	s_cbranch_scc1 .Lgb6_release
	s_sleep 1
	s_sub_i32 s11, s11, 1
	s_cmp_lg_u32 s11, 0
	s_cbranch_scc1 .Lgb6_topspin

.Lgb6_spin:
	s_sleep 1
	global_load_dword v2, v1, s[8:9] sc1
	s_waitcnt vmcnt(0)
	v_readfirstlane_b32 s7, v2
	s_cmp_gt_u32 s7, 6
	s_cbranch_scc1 .Lgb6_acq
	s_sub_i32 s11, s11, 1
	s_cmp_lg_u32 s11, 0
	s_cbranch_scc1 .Lgb6_spin
